# v45 + barrier elimination: redundant second workgroup barrier at the P4/P6 starts (1/rms table now written in the prologue) and the duplicate barrier before the deferred grid-barrier wait removed
# baseline (speedup 1.0000x reference)
.LBB0_165:
	s_mov_b64 s[100:101], exec
	v_readlane_b32 s98, v251, 41
	v_readlane_b32 s99, v251, 42
	s_and_b64 s[98:99], s[100:101], s[98:99]
	s_mov_b64 exec, s[98:99]
	s_cbranch_execz .Lmy_dw_done
	v_readlane_b32 s98, v251, 38
	v_readlane_b32 s99, v251, 39
	s_add_u32 s98, s98, 0x3500
	s_addc_u32 s99, s99, 0
	v_mov_b32_e32 v252, s98
	v_mov_b32_e32 v253, s99
	s_mov_b32 s99, 0

.LBB0_609:
	s_or_b64 exec, exec, s[18:19]
	v_readfirstlane_b32 s24, v0
	s_cmpk_gt_i32 s70, 0x3ff
	v_lshrrev_b32_e32 v148, 3, v0
	s_waitcnt lgkmcnt(0)
	s_cbranch_scc1 .LBB0_633
	s_cmp_gt_i32 s75, -1
	s_cbranch_scc0 .LBB0_612
	s_lshl_b32 s1, s75, 7
	s_cbranch_execz .LBB0_613
	s_branch .LBB0_614

.LBB0_747:
	s_or_b64 exec, exec, s[8:9]
	s_cmpk_gt_i32 s70, 0xff
	v_readfirstlane_b32 s36, v0
	s_waitcnt lgkmcnt(0)
	v_mov_b32_e32 v253, 0
	s_cbranch_scc1 .LBB0_767
	s_cmp_gt_i32 s75, -1
	s_cbranch_scc0 .LBB0_750
	s_lshl_b32 s4, s75, 5
	s_cbranch_execz .LBB0_751
	s_branch .LBB0_752
